# v12 + up-GEMM K-loop DMA issue via SGPR base + 32-bit voffset (no VALU address math in load segments), B read bases hoisted
# speedup vs baseline: 1.0155x; 1.0155x over previous
; #define PG8_STAGE(bufoff, gbase, voff) do { _Pragma("unroll") for (int _i = 0; _i < 2; ++_i) \
;         __builtin_amdgcn_global_load_lds((const unsigned*)((const char*)(gbase) + (voff)[_i]), (PG8_LAS unsigned*)(lds + (bufoff) + ldsw + _i * 8192), 16, 0, 0); } while (0)
; #define PG8_WAIT_V(n) asm volatile("s_waitcnt vmcnt(" #n ")" ::: "memory")
; #define PG8_BAR __builtin_amdgcn_s_barrier()
; template <class Epi, class Sched, bool ALIGN_EPI = false, bool SP2 = false>
; __device__ __forceinline__ void gemm_phase(PG8_LAS unsigned char* lds, const int tid, const Gemm g, const Sched& S, const Epi& E) {
;     ...
;     if constexpr (SP2) {
;         PG8_STAGE(PG8_SB(0, 0), cB, voffB); PG8_STAGE(PG8_SB(0, 1), cB + hstep, voffB); PG8_STAGE(PG8_SA(0, 0), cA, voffA); PG8_STAGE(PG8_SA(0, 1), cA + hstep, voffA);
;         if (wr == 1) PG8_BAR;
;         PG8_WAIT_V(2); PG8_BAR;
;         PG8_STAGE(PG8_SB(1, 0), cB + kstep, voffB); PG8_STAGE(PG8_SA(1, 0), cA + kstep, voffA); PG8_STAGE(PG8_SB(1, 1), cB + hstep + kstep, voffB);
;         PG8_WAIT_V(6); PG8_BAR;
.LBB0_418:
	s_and_b64 s[0:1], s[0:1], exec
	v_readlane_b32 s6, v251, 52
	s_cselect_b32 s0, 2, 0
	s_mul_i32 s1, s6, 3
	s_add_i32 s0, s0, s1
	v_readlane_b32 s7, v251, 53
	s_ashr_i32 s1, s0, 31
	s_lshl_b64 s[6:7], s[0:1], 17
	s_add_u32 s6, s8, s6
	s_addc_u32 s7, s9, s7
	s_mul_hi_i32 s1, s0, 0x16000
	s_mul_i32 s0, s0, 0x16000
	v_readlane_b32 s8, v251, 46
	s_add_u32 s8, s8, s0
	v_readlane_b32 s0, v251, 47
	s_addc_u32 s9, s0, s1
	s_lshl_b32 s0, s18, 5
	s_and_b32 s22, s0, 0x60
	s_add_i32 m0, s14, 0x18000
	v_lshl_add_u64 v[6:7], v[6:7], 0, s[36:37]
	s_lshl_b32 s21, s5, 13
	s_lshl_b32 s23, s22, 7
	s_waitcnt vmcnt(2)
	s_barrier
	global_load_lds_dwordx4 v[6:7], off
	v_lshl_add_u64 v[4:5], v[4:5], 0, s[36:37]
	s_add_i32 m0, s14, 0x1a000
	s_add_i32 s18, s14, 0x8000
	s_add_i32 s19, s14, 0xa000
	global_load_lds_dwordx4 v[4:5], off
	v_lshl_add_u64 v[0:1], v[0:1], 0, s[36:37]
	s_mov_b32 m0, s18
	s_add_u32 s0, s24, 0x40080
	global_load_lds_dwordx4 v[0:1], off
	v_lshl_add_u64 v[0:1], v[2:3], 0, s[36:37]
	s_mov_b32 m0, s19
	s_addc_u32 s1, s25, 0
	global_load_lds_dwordx4 v[0:1], off
	s_add_i32 m0, s14, 0x1c000
	v_lshl_add_u64 v[0:1], s[0:1], 0, v[168:169]
	global_load_lds_dwordx4 v[0:1], off
	v_lshl_add_u64 v[0:1], s[0:1], 0, v[144:145]
	s_add_i32 m0, s14, 0x1e000
	s_cmpk_lt_u32 s4, 0x100
	global_load_lds_dwordx4 v[0:1], off
	v_lshrrev_b32_e32 v0, 1, v182
	v_and_b32_e32 v0, 24, v0
	v_and_b32_e32 v1, 15, v182
	v_lshlrev_b32_e32 v2, 1, v0
	v_lshl_or_b32 v158, s5, 6, v1
	v_lshl_or_b32 v1, v1, 6, v2
	v_lshlrev_b32_e32 v2, 2, v182
	v_and_b32_e32 v2, 32, v2
	v_bitop3_b32 v3, v1, s21, v2 bitop3:0xde
	v_mov_b32_e32 v159, v254
	v_lshlrev_b32_e32 v1, 14, v12
	v_and_b32_e32 v1, 0xffff8000, v1
	v_lshl_add_u32 v1, v11, 11, v1
	v_and_b32_e32 v2, 1, v12
	v_lshl_or_b32 v1, v2, 6, v1
	v_mov_b32_e32 v150, v244
	v_lshlrev_b32_e32 v1, 14, v8
	v_and_b32_e32 v1, 0xffff8000, v1
	s_waitcnt vmcnt(6)
	v_lshl_add_u32 v1, v9, 11, v1
	v_and_b32_e32 v2, 1, v8
	v_lshl_or_b32 v1, v2, 6, v1
	v_readlane_b32 s0, v253, 61
	s_mov_b32 s20, 0
	s_cselect_b64 s[28:29], -1, 0
	v_or_b32_e32 v160, s22, v0
	v_mov_b32_e32 v151, v169
	v_mov_b32_e32 v152, v245
	v_mov_b32_e32 v153, v169
	v_mov_b32_e32 v161, v248
	v_add_u32_e32 v244, 0x10000, v254
	v_add_u32_e32 v245, 0x10000, v255
	s_lshl_b32 s21, s22, 2
	v_lshlrev_b32_e32 v162, 2, v0
	v_readlane_b32 s22, v253, 52
	s_mov_b32 s23, s0
	s_barrier
	v_readlane_b32 s1, v253, 62
	s_branch .LBB0_421

; #define PG8_STAGE(bufoff, gbase, voff) do { _Pragma("unroll") for (int _i = 0; _i < 2; ++_i) \
;         __builtin_amdgcn_global_load_lds((const unsigned*)((const char*)(gbase) + (voff)[_i]), (PG8_LAS unsigned*)(lds + (bufoff) + ldsw + _i * 8192), 16, 0, 0); } while (0)
; #define PG8_LDA(dst, b, h) do { _Pragma("unroll") for (int m = 0; m < 4; ++m) _Pragma("unroll") for (int k = 0; k < 2; ++k) dst[m][k] = *(const PG8_LAS bf16x8*)(lds + PG8_SA(b, h) + aoff + m * 2048 + k * 1024); } while (0)
; #define PG8_LDB(dst, b, h) do { _Pragma("unroll") for (int n = 0; n < 2; ++n) _Pragma("unroll") for (int k = 0; k < 2; ++k) dst[n][k] = *(const PG8_LAS bf16x8*)(lds + PG8_SB(b, h) + boff + n * 2048 + k * 1024); } while (0)
; #define PG8_MMA(ai, bj, At, Bt) do { __builtin_amdgcn_s_setprio(1); _Pragma("unroll") for (int m = 0; m < 4; ++m) _Pragma("unroll") for (int n = 0; n < 2; ++n) _Pragma("unroll") for (int k = 0; k < 2; ++k) \
;         acc[ai][bj][m][n] = __builtin_amdgcn_mfma_f32_16x16x32_bf16(Bt[n][k], At[m][k], acc[ai][bj][m][n], 0, 0, 0); __builtin_amdgcn_s_setprio(0); } while (0)
; #define PG8_WAIT_V(n) asm volatile("s_waitcnt vmcnt(" #n ")" ::: "memory")
; #define PG8_WAIT_L(n) asm volatile("s_waitcnt lgkmcnt(" #n ")" ::: "memory")
; #define PG8_BAR __builtin_amdgcn_s_barrier()
; #define PG8_SCHED __builtin_amdgcn_sched_barrier(0)
; template <class Epi, class Sched, bool ALIGN_EPI = false, bool SP2 = false>
; __device__ __forceinline__ void gemm_phase(PG8_LAS unsigned char* lds, const int tid, const Gemm g, const Sched& S, const Epi& E) {
;     ...
;             PG8_LDB(B0, 0, 0); PG8_LDB(B1, 0, 1); PG8_SCHED; PG8_LDA(At, 0, 0); PG8_STAGE(PG8_SA(1, 1), a1 + hstep, voffA);
;             PG8_WAIT_V(8); PG8_WAIT_L(0); PG8_BAR; PG8_MMA(0, 0, At, B0); PG8_MMA(0, 1, At, B1); PG8_BAR; PG8_SCHED;
;             PG8_LDA(At, 0, 1); PG8_STAGE(PG8_SB(0, 0), b2, voffB); PG8_STAGE(PG8_SB(0, 1), b2 + hstep, voffB); PG8_STAGE(PG8_SA(0, 0), a2, voffA);
;             PG8_WAIT_V(8); PG8_WAIT_L(0); PG8_BAR; PG8_MMA(1, 0, At, B0); PG8_MMA(1, 1, At, B1); PG8_BAR; PG8_SCHED;
.LBB0_426:
	s_add_u32 s24, s4, 0xfffc0080
	s_addc_u32 s25, s5, -1
	s_cmp_eq_u32 s48, 12
	s_cselect_b32 s27, s39, s25
	s_cselect_b32 s26, s41, s24
	s_cselect_b32 s25, s43, s47
	s_cselect_b32 s24, s42, s46
	ds_read_b128 v[64:67], v244
	ds_read_b128 v[68:71], v245
	ds_read_b128 v[72:75], v244 offset:2048
	ds_read_b128 v[76:79], v245 offset:2048
	ds_read_b128 v[154:157], v244 offset:16384
	ds_read_b128 v[164:167], v245 offset:16384
	ds_read_b128 v[186:189], v244 offset:18432
	ds_read_b128 v[190:193], v245 offset:18432
	s_add_i32 m0, s14, 0xc000
	ds_read_b128 v[194:197], v161
	ds_read_b128 v[198:201], v249
	ds_read_b128 v[202:205], v161 offset:2048
	ds_read_b128 v[206:209], v249 offset:2048
	ds_read_b128 v[210:213], v161 offset:4096
	ds_read_b128 v[214:217], v249 offset:4096
	ds_read_b128 v[218:221], v161 offset:6144
	ds_read_b128 v[230:233], v249 offset:6144
	global_load_lds_dwordx4 v150, s[4:5]
	s_add_i32 m0, s14, 0xe000
	s_nop 0
	global_load_lds_dwordx4 v152, s[4:5]
	s_waitcnt vmcnt(8)
	s_waitcnt lgkmcnt(0)
	s_barrier
	s_setprio 1
	s_waitcnt lgkmcnt(0)
	v_mfma_f32_16x16x32_bf16 v[140:143], v[64:67], v[194:197], v[140:143]
	v_mfma_f32_16x16x32_bf16 v[136:139], v[72:75], v[194:197], v[136:139]
	v_mfma_f32_16x16x32_bf16 v[124:127], v[64:67], v[202:205], v[124:127]
	v_mfma_f32_16x16x32_bf16 v[120:123], v[72:75], v[202:205], v[120:123]
	v_mfma_f32_16x16x32_bf16 v[108:111], v[64:67], v[210:213], v[108:111]
	v_mfma_f32_16x16x32_bf16 v[104:107], v[72:75], v[210:213], v[104:107]
	v_mfma_f32_16x16x32_bf16 v[92:95], v[64:67], v[218:221], v[92:95]
	v_mfma_f32_16x16x32_bf16 v[88:91], v[72:75], v[218:221], v[88:91]
	v_mfma_f32_16x16x32_bf16 v[140:143], v[68:71], v[198:201], v[140:143]
	v_mfma_f32_16x16x32_bf16 v[136:139], v[76:79], v[198:201], v[136:139]
	v_mfma_f32_16x16x32_bf16 v[124:127], v[68:71], v[206:209], v[124:127]
	v_mfma_f32_16x16x32_bf16 v[120:123], v[76:79], v[206:209], v[120:123]
	v_mfma_f32_16x16x32_bf16 v[108:111], v[68:71], v[214:217], v[108:111]
	v_mfma_f32_16x16x32_bf16 v[104:107], v[76:79], v[214:217], v[104:107]
	v_mfma_f32_16x16x32_bf16 v[92:95], v[68:71], v[230:233], v[92:95]
	v_mfma_f32_16x16x32_bf16 v[88:91], v[76:79], v[230:233], v[88:91]
	s_setprio 0
	s_setprio 1
	v_mfma_f32_16x16x32_bf16 v[132:135], v[154:157], v[194:197], v[132:135]
	v_mfma_f32_16x16x32_bf16 v[128:131], v[186:189], v[194:197], v[128:131]
	v_mfma_f32_16x16x32_bf16 v[116:119], v[154:157], v[202:205], v[116:119]
	v_mfma_f32_16x16x32_bf16 v[112:115], v[186:189], v[202:205], v[112:115]
	v_mfma_f32_16x16x32_bf16 v[100:103], v[154:157], v[210:213], v[100:103]
	v_mfma_f32_16x16x32_bf16 v[96:99], v[186:189], v[210:213], v[96:99]
	v_mfma_f32_16x16x32_bf16 v[84:87], v[154:157], v[218:221], v[84:87]
	v_mfma_f32_16x16x32_bf16 v[80:83], v[186:189], v[218:221], v[80:83]
	v_mfma_f32_16x16x32_bf16 v[132:135], v[164:167], v[198:201], v[132:135]
	v_mfma_f32_16x16x32_bf16 v[128:131], v[190:193], v[198:201], v[128:131]
	v_mfma_f32_16x16x32_bf16 v[116:119], v[164:167], v[206:209], v[116:119]
	v_mfma_f32_16x16x32_bf16 v[112:115], v[190:193], v[206:209], v[112:115]
	v_mfma_f32_16x16x32_bf16 v[100:103], v[164:167], v[214:217], v[100:103]
	v_mfma_f32_16x16x32_bf16 v[96:99], v[190:193], v[214:217], v[96:99]
	v_mfma_f32_16x16x32_bf16 v[84:87], v[164:167], v[230:233], v[84:87]
	v_mfma_f32_16x16x32_bf16 v[80:83], v[190:193], v[230:233], v[80:83]
	s_setprio 0
	s_barrier
	s_add_i32 m0, s12, 0x10000
	ds_read_b128 v[194:197], v161 offset:16384
	ds_read_b128 v[198:201], v249 offset:16384
	ds_read_b128 v[202:205], v161 offset:18432
	ds_read_b128 v[206:209], v249 offset:18432
	ds_read_b128 v[210:213], v161 offset:20480
	ds_read_b128 v[214:217], v249 offset:20480
	ds_read_b128 v[218:221], v161 offset:22528
	ds_read_b128 v[230:233], v249 offset:22528
	global_load_lds_dwordx4 v168, s[24:25]
	s_add_i32 m0, s12, 0x12000
	s_add_u32 s50, s24, 0x40000
	s_addc_u32 s51, s25, 0
	global_load_lds_dwordx4 v144, s[24:25]
	s_add_i32 m0, s12, 0x14000
	s_nop 0
	global_load_lds_dwordx4 v168, s[50:51]
	s_add_i32 m0, s12, 0x16000
	s_nop 0
	global_load_lds_dwordx4 v144, s[50:51]
	s_mov_b32 m0, s14
	s_nop 0
	global_load_lds_dwordx4 v148, s[26:27]
	s_mov_b32 m0, s15
	s_nop 0
	global_load_lds_dwordx4 v146, s[26:27]
	s_waitcnt vmcnt(8)
	s_waitcnt lgkmcnt(0)
	s_barrier
	s_setprio 1
	s_waitcnt lgkmcnt(0)
	v_mfma_f32_16x16x32_bf16 v[60:63], v[64:67], v[194:197], v[60:63]
	v_mfma_f32_16x16x32_bf16 v[56:59], v[72:75], v[194:197], v[56:59]
	v_mfma_f32_16x16x32_bf16 v[44:47], v[64:67], v[202:205], v[44:47]
	v_mfma_f32_16x16x32_bf16 v[40:43], v[72:75], v[202:205], v[40:43]
	v_mfma_f32_16x16x32_bf16 v[28:31], v[64:67], v[210:213], v[28:31]
	v_mfma_f32_16x16x32_bf16 v[24:27], v[72:75], v[210:213], v[24:27]
	v_mfma_f32_16x16x32_bf16 v[12:15], v[64:67], v[218:221], v[12:15]
	v_mfma_f32_16x16x32_bf16 v[8:11], v[72:75], v[218:221], v[8:11]
	v_mfma_f32_16x16x32_bf16 v[60:63], v[68:71], v[198:201], v[60:63]
	v_mfma_f32_16x16x32_bf16 v[56:59], v[76:79], v[198:201], v[56:59]
	v_mfma_f32_16x16x32_bf16 v[44:47], v[68:71], v[206:209], v[44:47]
	v_mfma_f32_16x16x32_bf16 v[40:43], v[76:79], v[206:209], v[40:43]
	v_mfma_f32_16x16x32_bf16 v[28:31], v[68:71], v[214:217], v[28:31]
	v_mfma_f32_16x16x32_bf16 v[24:27], v[76:79], v[214:217], v[24:27]
	v_mfma_f32_16x16x32_bf16 v[12:15], v[68:71], v[230:233], v[12:15]
	v_mfma_f32_16x16x32_bf16 v[8:11], v[76:79], v[230:233], v[8:11]
	s_setprio 0
	s_setprio 1
	v_mfma_f32_16x16x32_bf16 v[52:55], v[154:157], v[194:197], v[52:55]
	v_mfma_f32_16x16x32_bf16 v[48:51], v[186:189], v[194:197], v[48:51]
	v_mfma_f32_16x16x32_bf16 v[36:39], v[154:157], v[202:205], v[36:39]
	v_mfma_f32_16x16x32_bf16 v[32:35], v[186:189], v[202:205], v[32:35]
	v_mfma_f32_16x16x32_bf16 v[20:23], v[154:157], v[210:213], v[20:23]
	v_mfma_f32_16x16x32_bf16 v[16:19], v[186:189], v[210:213], v[16:19]
	v_mfma_f32_16x16x32_bf16 v[4:7], v[154:157], v[218:221], v[4:7]
	v_mfma_f32_16x16x32_bf16 v[0:3], v[186:189], v[218:221], v[0:3]
	v_mfma_f32_16x16x32_bf16 v[52:55], v[164:167], v[198:201], v[52:55]
	v_mfma_f32_16x16x32_bf16 v[48:51], v[190:193], v[198:201], v[48:51]
	v_mfma_f32_16x16x32_bf16 v[36:39], v[164:167], v[206:209], v[36:39]
	v_mfma_f32_16x16x32_bf16 v[32:35], v[190:193], v[206:209], v[32:35]
	v_mfma_f32_16x16x32_bf16 v[20:23], v[164:167], v[214:217], v[20:23]
	v_mfma_f32_16x16x32_bf16 v[16:19], v[190:193], v[214:217], v[16:19]
	v_mfma_f32_16x16x32_bf16 v[4:7], v[164:167], v[230:233], v[4:7]
	v_mfma_f32_16x16x32_bf16 v[0:3], v[190:193], v[230:233], v[0:3]
	s_setprio 0
	s_barrier
; #define PG8_STAGE(bufoff, gbase, voff) do { _Pragma("unroll") for (int _i = 0; _i < 2; ++_i) \
;         __builtin_amdgcn_global_load_lds((const unsigned*)((const char*)(gbase) + (voff)[_i]), (PG8_LAS unsigned*)(lds + (bufoff) + ldsw + _i * 8192), 16, 0, 0); } while (0)
; #define PG8_LDA(dst, b, h) do { _Pragma("unroll") for (int m = 0; m < 4; ++m) _Pragma("unroll") for (int k = 0; k < 2; ++k) dst[m][k] = *(const PG8_LAS bf16x8*)(lds + PG8_SA(b, h) + aoff + m * 2048 + k * 1024); } while (0)
; #define PG8_LDB(dst, b, h) do { _Pragma("unroll") for (int n = 0; n < 2; ++n) _Pragma("unroll") for (int k = 0; k < 2; ++k) dst[n][k] = *(const PG8_LAS bf16x8*)(lds + PG8_SB(b, h) + boff + n * 2048 + k * 1024); } while (0)
; #define PG8_MMA(ai, bj, At, Bt) do { __builtin_amdgcn_s_setprio(1); _Pragma("unroll") for (int m = 0; m < 4; ++m) _Pragma("unroll") for (int n = 0; n < 2; ++n) _Pragma("unroll") for (int k = 0; k < 2; ++k) \
;         acc[ai][bj][m][n] = __builtin_amdgcn_mfma_f32_16x16x32_bf16(Bt[n][k], At[m][k], acc[ai][bj][m][n], 0, 0, 0); __builtin_amdgcn_s_setprio(0); } while (0)
; #define PG8_WAIT_V(n) asm volatile("s_waitcnt vmcnt(" #n ")" ::: "memory")
; #define PG8_WAIT_L(n) asm volatile("s_waitcnt lgkmcnt(" #n ")" ::: "memory")
; #define PG8_BAR __builtin_amdgcn_s_barrier()
; #define PG8_SCHED __builtin_amdgcn_sched_barrier(0)
; template <class Epi, class Sched, bool ALIGN_EPI = false, bool SP2 = false>
; __device__ __forceinline__ void gemm_phase(PG8_LAS unsigned char* lds, const int tid, const Gemm g, const Sched& S, const Epi& E) {
;     ...
;             PG8_LDB(B0, 1, 0); PG8_LDB(B1, 1, 1); PG8_SCHED; PG8_LDA(At, 1, 0); PG8_STAGE(PG8_SA(0, 1), a2 + hstep, voffA);
;             PG8_WAIT_V(8); PG8_WAIT_L(0); PG8_BAR; PG8_MMA(0, 0, At, B0); PG8_MMA(0, 1, At, B1); PG8_BAR; PG8_SCHED;
;             PG8_LDA(At, 1, 1); PG8_STAGE(PG8_SB(1, 0), b3, voffB); PG8_STAGE(PG8_SB(1, 1), b3 + hstep, voffB); PG8_STAGE(PG8_SA(1, 0), a3, voffA);
;             PG8_WAIT_V(8); PG8_WAIT_L(0); PG8_BAR; PG8_MMA(1, 0, At, B0); PG8_MMA(1, 1, At, B1); PG8_BAR; PG8_SCHED;
	ds_read_b128 v[64:67], v244 offset:32768
	ds_read_b128 v[68:71], v245 offset:32768
	ds_read_b128 v[72:75], v244 offset:34816
	ds_read_b128 v[76:79], v245 offset:34816
	ds_read_b128 v[154:157], v244 offset:49152
	ds_read_b128 v[164:167], v245 offset:49152
	ds_read_b128 v[186:189], v244 offset:51200
	ds_read_b128 v[190:193], v245 offset:51200
	s_add_u32 s26, s26, 0x40000
	s_addc_u32 s27, s27, 0
	s_mov_b32 m0, s16
	ds_read_b128 v[194:197], v161 offset:32768
	ds_read_b128 v[198:201], v249 offset:32768
	ds_read_b128 v[202:205], v161 offset:34816
	ds_read_b128 v[206:209], v249 offset:34816
	ds_read_b128 v[210:213], v161 offset:36864
	ds_read_b128 v[214:217], v249 offset:36864
	ds_read_b128 v[218:221], v161 offset:38912
	ds_read_b128 v[230:233], v249 offset:38912
	global_load_lds_dwordx4 v148, s[26:27]
	s_mov_b32 m0, s17
	s_nop 0
	global_load_lds_dwordx4 v146, s[26:27]
	s_waitcnt vmcnt(8)
	s_waitcnt lgkmcnt(0)
	s_barrier
	s_setprio 1
	s_waitcnt lgkmcnt(0)
	v_mfma_f32_16x16x32_bf16 v[140:143], v[64:67], v[194:197], v[140:143]
	v_mfma_f32_16x16x32_bf16 v[136:139], v[72:75], v[194:197], v[136:139]
	v_mfma_f32_16x16x32_bf16 v[124:127], v[64:67], v[202:205], v[124:127]
	v_mfma_f32_16x16x32_bf16 v[120:123], v[72:75], v[202:205], v[120:123]
	v_mfma_f32_16x16x32_bf16 v[108:111], v[64:67], v[210:213], v[108:111]
	v_mfma_f32_16x16x32_bf16 v[104:107], v[72:75], v[210:213], v[104:107]
	v_mfma_f32_16x16x32_bf16 v[92:95], v[64:67], v[218:221], v[92:95]
	v_mfma_f32_16x16x32_bf16 v[88:91], v[72:75], v[218:221], v[88:91]
	v_mfma_f32_16x16x32_bf16 v[140:143], v[68:71], v[198:201], v[140:143]
	v_mfma_f32_16x16x32_bf16 v[136:139], v[76:79], v[198:201], v[136:139]
	v_mfma_f32_16x16x32_bf16 v[124:127], v[68:71], v[206:209], v[124:127]
	v_mfma_f32_16x16x32_bf16 v[120:123], v[76:79], v[206:209], v[120:123]
	v_mfma_f32_16x16x32_bf16 v[108:111], v[68:71], v[214:217], v[108:111]
	v_mfma_f32_16x16x32_bf16 v[104:107], v[76:79], v[214:217], v[104:107]
	v_mfma_f32_16x16x32_bf16 v[92:95], v[68:71], v[230:233], v[92:95]
	v_mfma_f32_16x16x32_bf16 v[88:91], v[76:79], v[230:233], v[88:91]
	s_setprio 0
	s_setprio 1
	v_mfma_f32_16x16x32_bf16 v[132:135], v[154:157], v[194:197], v[132:135]
	v_mfma_f32_16x16x32_bf16 v[128:131], v[186:189], v[194:197], v[128:131]
	v_mfma_f32_16x16x32_bf16 v[116:119], v[154:157], v[202:205], v[116:119]
	v_mfma_f32_16x16x32_bf16 v[112:115], v[186:189], v[202:205], v[112:115]
	v_mfma_f32_16x16x32_bf16 v[100:103], v[154:157], v[210:213], v[100:103]
	v_mfma_f32_16x16x32_bf16 v[96:99], v[186:189], v[210:213], v[96:99]
	v_mfma_f32_16x16x32_bf16 v[84:87], v[154:157], v[218:221], v[84:87]
	v_mfma_f32_16x16x32_bf16 v[80:83], v[186:189], v[218:221], v[80:83]
	v_mfma_f32_16x16x32_bf16 v[132:135], v[164:167], v[198:201], v[132:135]
	v_mfma_f32_16x16x32_bf16 v[128:131], v[190:193], v[198:201], v[128:131]
	v_mfma_f32_16x16x32_bf16 v[116:119], v[164:167], v[206:209], v[116:119]
	v_mfma_f32_16x16x32_bf16 v[112:115], v[190:193], v[206:209], v[112:115]
	v_mfma_f32_16x16x32_bf16 v[100:103], v[164:167], v[214:217], v[100:103]
	v_mfma_f32_16x16x32_bf16 v[96:99], v[190:193], v[214:217], v[96:99]
	v_mfma_f32_16x16x32_bf16 v[84:87], v[164:167], v[230:233], v[84:87]
	v_mfma_f32_16x16x32_bf16 v[80:83], v[190:193], v[230:233], v[80:83]
	s_setprio 0
	s_barrier
	s_add_u32 s94, s24, 0x80
	s_addc_u32 s95, s25, 0
	s_add_i32 m0, s12, 0x18000
	ds_read_b128 v[194:197], v161 offset:49152
	ds_read_b128 v[198:201], v249 offset:49152
	ds_read_b128 v[202:205], v161 offset:51200
	ds_read_b128 v[206:209], v249 offset:51200
	ds_read_b128 v[210:213], v161 offset:53248
	ds_read_b128 v[214:217], v249 offset:53248
	ds_read_b128 v[218:221], v161 offset:55296
	ds_read_b128 v[230:233], v249 offset:55296
	global_load_lds_dwordx4 v168, s[94:95]
	s_add_i32 m0, s12, 0x1a000
	s_add_u32 s24, s24, 0x40080
	s_addc_u32 s25, s25, 0
	global_load_lds_dwordx4 v144, s[94:95]
	s_add_i32 m0, s12, 0x1c000
	s_add_u32 s92, s26, 0xfffc0080
	s_addc_u32 s93, s27, -1
	global_load_lds_dwordx4 v168, s[24:25]
	s_add_i32 m0, s12, 0x1e000
	s_nop 0
	global_load_lds_dwordx4 v144, s[24:25]
	s_mov_b32 m0, s18
	s_nop 0
	global_load_lds_dwordx4 v148, s[92:93]
	s_mov_b32 m0, s19
	s_nop 0
	global_load_lds_dwordx4 v146, s[92:93]
	s_waitcnt vmcnt(8)
	s_waitcnt lgkmcnt(0)
	s_barrier
	s_setprio 1
	s_waitcnt lgkmcnt(0)
	v_mfma_f32_16x16x32_bf16 v[60:63], v[64:67], v[194:197], v[60:63]
	v_mfma_f32_16x16x32_bf16 v[56:59], v[72:75], v[194:197], v[56:59]
	v_mfma_f32_16x16x32_bf16 v[44:47], v[64:67], v[202:205], v[44:47]
	v_mfma_f32_16x16x32_bf16 v[40:43], v[72:75], v[202:205], v[40:43]
	v_mfma_f32_16x16x32_bf16 v[28:31], v[64:67], v[210:213], v[28:31]
	v_mfma_f32_16x16x32_bf16 v[24:27], v[72:75], v[210:213], v[24:27]
	v_mfma_f32_16x16x32_bf16 v[12:15], v[64:67], v[218:221], v[12:15]
	v_mfma_f32_16x16x32_bf16 v[8:11], v[72:75], v[218:221], v[8:11]
	v_mfma_f32_16x16x32_bf16 v[60:63], v[68:71], v[198:201], v[60:63]
	v_mfma_f32_16x16x32_bf16 v[56:59], v[76:79], v[198:201], v[56:59]
	v_mfma_f32_16x16x32_bf16 v[44:47], v[68:71], v[206:209], v[44:47]
	v_mfma_f32_16x16x32_bf16 v[40:43], v[76:79], v[206:209], v[40:43]
	v_mfma_f32_16x16x32_bf16 v[28:31], v[68:71], v[214:217], v[28:31]
	v_mfma_f32_16x16x32_bf16 v[24:27], v[76:79], v[214:217], v[24:27]
	v_mfma_f32_16x16x32_bf16 v[12:15], v[68:71], v[230:233], v[12:15]
	v_mfma_f32_16x16x32_bf16 v[8:11], v[76:79], v[230:233], v[8:11]
	s_setprio 0
	s_setprio 1
	v_mfma_f32_16x16x32_bf16 v[52:55], v[154:157], v[194:197], v[52:55]
	v_mfma_f32_16x16x32_bf16 v[48:51], v[186:189], v[194:197], v[48:51]
	v_mfma_f32_16x16x32_bf16 v[36:39], v[154:157], v[202:205], v[36:39]
	v_mfma_f32_16x16x32_bf16 v[32:35], v[186:189], v[202:205], v[32:35]
	v_mfma_f32_16x16x32_bf16 v[20:23], v[154:157], v[210:213], v[20:23]
	v_mfma_f32_16x16x32_bf16 v[16:19], v[186:189], v[210:213], v[16:19]
	v_mfma_f32_16x16x32_bf16 v[4:7], v[154:157], v[218:221], v[4:7]
	v_mfma_f32_16x16x32_bf16 v[0:3], v[186:189], v[218:221], v[0:3]
	v_mfma_f32_16x16x32_bf16 v[52:55], v[164:167], v[198:201], v[52:55]
	v_mfma_f32_16x16x32_bf16 v[48:51], v[190:193], v[198:201], v[48:51]
	v_mfma_f32_16x16x32_bf16 v[36:39], v[164:167], v[206:209], v[36:39]
	v_mfma_f32_16x16x32_bf16 v[32:35], v[190:193], v[206:209], v[32:35]
	v_mfma_f32_16x16x32_bf16 v[20:23], v[164:167], v[214:217], v[20:23]
	v_mfma_f32_16x16x32_bf16 v[16:19], v[190:193], v[214:217], v[16:19]
	v_mfma_f32_16x16x32_bf16 v[4:7], v[164:167], v[230:233], v[4:7]
	v_mfma_f32_16x16x32_bf16 v[0:3], v[190:193], v[230:233], v[0:3]
	s_setprio 0
	s_barrier
	s_add_i32 s48, s48, 2
	s_add_u32 s4, s4, 0x100
	s_addc_u32 s5, s5, 0
	s_add_u32 s46, s46, 0x100
	s_addc_u32 s47, s47, 0
	s_cmp_gt_u32 s48, 13
	s_cbranch_scc0 .LBB0_426
	s_and_b64 vcc, exec, s[28:29]
	s_cbranch_vccz .LBB0_429
	s_barrier
